# baseline (speedup 1.0000x reference)
.LBB0_1529:
	s_or_b64 exec, exec, s[4:5]
	s_waitcnt lgkmcnt(0)
	v_mov_b32_e32 v0, 0
	s_barrier
	s_nop 0
	v_mbcnt_lo_u32_b32 v0, -1, v0
	v_mbcnt_hi_u32_b32 v0, -1, v0
	v_add_u32_e32 v0, s33, v0
	s_load_dwordx8 s[4:11], s[0:1], 0x80
	v_and_b32_e32 v1, 63, v0
	v_lshlrev_b32_e32 v2, 2, v1
	s_waitcnt lgkmcnt(0)
	global_load_dword v3, v2, s[4:5]
	global_load_dword v4, v2, s[6:7]
	global_load_dword v5, v2, s[8:9]
	global_load_dword v6, v2, s[10:11]
	v_mbcnt_hi_u32_b32 v2, -1, v186
	v_and_b32_e32 v7, 64, v2
	v_xor_b32_e32 v8, 1, v2
	v_add_u32_e32 v7, 64, v7
	v_cmp_lt_i32_e32 vcc, v8, v7
	v_xor_b32_e32 v9, 2, v2
	v_xor_b32_e32 v12, 4, v2
	v_cndmask_b32_e32 v8, v2, v8, vcc
	v_lshlrev_b32_e32 v10, 2, v8
	v_cmp_lt_i32_e32 vcc, v9, v7
	v_xor_b32_e32 v13, 8, v2
	v_xor_b32_e32 v14, 16, v2
	v_cndmask_b32_e32 v9, v2, v9, vcc
	v_cmp_lt_i32_e32 vcc, v12, v7
	v_xor_b32_e32 v15, 32, v2
	v_readfirstlane_b32 s4, v0
	s_ashr_i32 s4, s4, 6
	s_add_i32 s4, s4, s76
	s_cmpk_gt_i32 s4, 0x3fff
	s_waitcnt vmcnt(2)
	v_mul_f32_e32 v8, v3, v4
	ds_bpermute_b32 v8, v10, v8
	s_waitcnt vmcnt(0)
	v_mul_f32_e32 v11, v5, v6
	ds_bpermute_b32 v16, v10, v11
	v_lshlrev_b32_e32 v11, 2, v9
	s_waitcnt lgkmcnt(1)
	v_fmac_f32_e32 v8, v3, v4
	ds_bpermute_b32 v3, v11, v8
	s_waitcnt lgkmcnt(1)
	v_fmac_f32_e32 v16, v5, v6
	ds_bpermute_b32 v4, v11, v16
	v_cndmask_b32_e32 v5, v2, v12, vcc
	v_lshlrev_b32_e32 v12, 2, v5
	s_waitcnt lgkmcnt(1)
	v_add_f32_e32 v3, v8, v3
	ds_bpermute_b32 v5, v12, v3
	s_waitcnt lgkmcnt(1)
	v_add_f32_e32 v4, v16, v4
	ds_bpermute_b32 v6, v12, v4
	v_cmp_lt_i32_e32 vcc, v13, v7
	s_waitcnt lgkmcnt(1)
	v_add_f32_e32 v3, v3, v5
	v_cndmask_b32_e32 v8, v2, v13, vcc
	v_lshlrev_b32_e32 v13, 2, v8
	s_waitcnt lgkmcnt(0)
	v_add_f32_e32 v4, v4, v6
	ds_bpermute_b32 v5, v13, v3
	ds_bpermute_b32 v6, v13, v4
	v_cmp_lt_i32_e32 vcc, v14, v7
	s_waitcnt lgkmcnt(1)
	v_add_f32_e32 v3, v3, v5
	v_cndmask_b32_e32 v8, v2, v14, vcc
	v_lshlrev_b32_e32 v149, 2, v8
	s_waitcnt lgkmcnt(0)
	v_add_f32_e32 v5, v4, v6
	ds_bpermute_b32 v4, v149, v3
	ds_bpermute_b32 v6, v149, v5
	v_cmp_lt_i32_e32 vcc, v15, v7
	v_mov_b32_e32 v14, 0
	s_waitcnt lgkmcnt(1)
	v_add_f32_e32 v4, v3, v4
	v_cndmask_b32_e32 v2, v2, v15, vcc
	v_lshlrev_b32_e32 v153, 2, v2
	s_waitcnt lgkmcnt(0)
	v_add_f32_e32 v2, v5, v6
	ds_bpermute_b32 v5, v153, v4
	ds_bpermute_b32 v3, v153, v2
	s_cbranch_scc1 .LBB0_1532
	s_load_dwordx2 s[6:7], s[0:1], 0xa0
	v_lshlrev_b32_e32 v6, 4, v0
	v_and_b32_e32 v6, 0x1f0, v6
	s_waitcnt lgkmcnt(0)
	v_add_f32_e32 v4, v4, v5
	s_mov_b32 s11, 0x3fb8aa3b
	global_load_dwordx4 v[16:19], v6, s[6:7]
	v_add_f32_e32 v6, v2, v3
	v_mul_f32_e32 v7, 0x3fb8aa3b, v4
	v_mul_f32_e32 v8, 0x3fb8aa3b, v6
	v_fma_f32 v9, v4, s11, -v7
	v_rndne_f32_e32 v20, v7
	v_fma_f32 v21, v6, s11, -v8
	v_rndne_f32_e32 v22, v8
	v_fmac_f32_e32 v9, 0x32a5705f, v4
	v_sub_f32_e32 v7, v7, v20
	v_fmac_f32_e32 v21, 0x32a5705f, v6
	v_sub_f32_e32 v8, v8, v22
	v_add_f32_e32 v7, v7, v9
	v_cvt_i32_f32_e32 v20, v20
	v_add_f32_e32 v8, v8, v21
	v_exp_f32_e32 v7, v7
	v_cvt_i32_f32_e32 v22, v22
	v_exp_f32_e32 v8, v8
	s_mov_b32 s24, 0xc2ce8ed0
	v_ldexp_f32 v7, v7, v20
	v_cmp_ngt_f32_e32 vcc, s24, v4
	s_mov_b32 s25, 0x42b17218
	v_ldexp_f32 v8, v8, v22
	v_cndmask_b32_e32 v7, 0, v7, vcc
	v_cmp_ngt_f32_e32 vcc, s24, v6
	v_mov_b32_e32 v5, 0x7f800000
	v_lshlrev_b32_e32 v1, 3, v1
	v_cndmask_b32_e32 v8, 0, v8, vcc
	v_cmp_nlt_f32_e32 vcc, s25, v4
	s_ashr_i32 s5, s4, 31
	v_and_b32_e32 v2, 32, v0
	v_lshlrev_b32_e32 v0, 3, v0
	v_cndmask_b32_e32 v4, v5, v7, vcc
	v_cmp_nlt_f32_e32 vcc, s25, v6
	v_and_b32_e32 v3, 0x100, v1
	s_lshl_b64 s[20:21], s[4:5], 12
	v_lshlrev_b32_e32 v1, 4, v2
	v_and_b32_e32 v2, 0xf8, v0
	s_lshl_b64 s[22:23], s[4:5], 11
	v_cndmask_b32_e32 v5, v5, v8, vcc
	v_or3_b32 v0, s20, v1, v2
	v_mov_b32_e32 v1, s21
	v_or3_b32 v2, s22, v3, v2
	v_mov_b32_e32 v3, s23
	v_sub_f32_e32 v4, v4, v5
	s_mov_b32 s10, 0x3f24fd5c
	s_mov_b64 s[12:13], 0xb900800
	s_ashr_i32 s35, s34, 31
	s_mov_b64 s[18:19], 0x5800400
	v_lshl_add_u64 v[0:1], s[14:15], 0, v[0:1]
	v_lshl_add_u64 v[2:3], s[14:15], 0, v[2:3]
	v_add_f32_e32 v4, 0x3eb60549, v4
	v_mov_b32_e32 v15, 0x358637bd
	s_lshl_b64 s[6:7], s[34:35], 12
	s_lshl_b64 s[8:9], s[34:35], 11
	v_lshl_add_u64 v[0:1], v[0:1], 0, s[12:13]
	v_lshl_add_u64 v[2:3], v[2:3], 0, s[18:19]
	v_mov_b32_e32 v5, v4
	s_mov_b32 s5, 0x800000
	s_waitcnt vmcnt(0)
	v_pk_mul_f32 v[6:7], v[18:19], s[10:11] op_sel_hi:[1,0]
	v_pk_mul_f32 v[8:9], v[16:17], s[10:11] op_sel_hi:[1,0]
	global_load_dwordx2 v[24:25], v[0:1], off offset:-2048
	global_load_dwordx2 v[26:27], v[0:1], off offset:-1792
	global_load_dwordx2 v[28:29], v[0:1], off offset:-1024
	global_load_dwordx2 v[30:31], v[0:1], off offset:-768
	global_load_dwordx2 v[32:33], v[0:1], off
	global_load_dwordx2 v[34:35], v[0:1], off offset:256
	global_load_dwordx2 v[36:37], v[0:1], off offset:1024
	global_load_dwordx2 v[38:39], v[0:1], off offset:1280
	v_lshl_add_u64 v[0:1], v[0:1], 0, s[6:7]
	s_waitcnt vmcnt(0)
	s_mov_b32 s92, 0x55555555
	s_mov_b32 s93, 0x55555555

.Lcb_nopf:
	v_mov_b64_e32 v[16:17], v[24:25]
	v_mov_b64_e32 v[18:19], v[26:27]
	v_lshlrev_b32_e32 v20, 16, v16
	v_and_b32_e32 v21, 0xffff0000, v16
	v_lshlrev_b32_e32 v22, 16, v18
	v_and_b32_e32 v23, 0xffff0000, v18
	v_lshlrev_b32_e32 v16, 16, v17
	v_and_b32_e32 v17, 0xffff0000, v17
	v_lshlrev_b32_e32 v18, 16, v19
	v_and_b32_e32 v19, 0xffff0000, v19
	v_pk_fma_f32 v[20:21], v[4:5], v[22:23], v[20:21] neg_lo:[1,0,0] neg_hi:[1,0,0]
	v_pk_fma_f32 v[16:17], v[4:5], v[18:19], v[16:17] neg_lo:[1,0,0] neg_hi:[1,0,0]
	v_mov_b32_e32 v22, v21
	v_mov_b32_e32 v23, v17
	v_mov_b32_e32 v18, v20
	v_mov_b32_e32 v19, v16
	v_pk_mul_f32 v[22:23], v[22:23], v[22:23]
	s_nop 0
	v_pk_fma_f32 v[18:19], v[18:19], v[18:19], v[22:23]
	s_nop 0
	v_add_f32_e32 v18, v18, v19
	ds_bpermute_b32 v19, v10, v18
	s_waitcnt lgkmcnt(0)
	v_add_f32_e32 v18, v18, v19
	ds_bpermute_b32 v19, v11, v18
	s_waitcnt lgkmcnt(0)
	v_add_f32_e32 v18, v18, v19
	ds_bpermute_b32 v19, v12, v18
	s_waitcnt lgkmcnt(0)
	v_add_f32_e32 v18, v18, v19
	ds_bpermute_b32 v19, v13, v18
	s_waitcnt lgkmcnt(0)
	v_add_f32_e32 v18, v18, v19
	ds_bpermute_b32 v19, v149, v18
	s_waitcnt lgkmcnt(0)
	v_add_f32_e32 v18, v18, v19
	v_fmamk_f32 v18, v18, 0x3c000000, v15
	v_mul_f32_e32 v19, 0x4b800000, v18
	v_cmp_gt_f32_e32 vcc, s5, v18
	s_nop 1
	v_cndmask_b32_e32 v18, v18, v19, vcc
	v_rsq_f32_e32 v18, v18
	s_nop 0
	v_mul_f32_e32 v19, 0x45800000, v18
	v_cndmask_b32_e32 v18, v18, v19, vcc
	v_pk_mul_f32 v[20:21], v[20:21], v[18:19] op_sel_hi:[1,0]
	v_pk_mul_f32 v[16:17], v[16:17], v[18:19] op_sel_hi:[1,0]
	v_pk_mul_f32 v[18:19], v[8:9], v[20:21]
	v_pk_mul_f32 v[16:17], v[6:7], v[16:17]
	v_cvt_pk_bf16_f32 v18, v18, v19
	s_nop 0
	v_cvt_pk_bf16_f32 v19, v16, v17
	s_nop 1
	v_mov_b32_dpp v60, v18 quad_perm:[1,0,3,2] row_mask:0xf bank_mask:0xf
	v_mov_b32_dpp v61, v19 quad_perm:[1,0,3,2] row_mask:0xf bank_mask:0xf
	v_mov_b32_e32 v58, v18
	v_mov_b32_e32 v59, v19
	s_mov_b64 s[94:95], exec
	s_mov_b64 exec, s[92:93]
	global_store_dwordx4 v[2:3], v[58:61], off offset:-1024 sc0 sc1
	s_mov_b64 exec, s[94:95]
	v_mov_b64_e32 v[16:17], v[28:29]
	v_mov_b64_e32 v[18:19], v[30:31]
	v_lshlrev_b32_e32 v20, 16, v16
	v_and_b32_e32 v21, 0xffff0000, v16
	v_lshlrev_b32_e32 v22, 16, v18
	v_and_b32_e32 v23, 0xffff0000, v18
	v_lshlrev_b32_e32 v16, 16, v17
	v_and_b32_e32 v17, 0xffff0000, v17
	v_lshlrev_b32_e32 v18, 16, v19
	v_and_b32_e32 v19, 0xffff0000, v19
	v_pk_fma_f32 v[20:21], v[4:5], v[22:23], v[20:21] neg_lo:[1,0,0] neg_hi:[1,0,0]
	v_pk_fma_f32 v[16:17], v[4:5], v[18:19], v[16:17] neg_lo:[1,0,0] neg_hi:[1,0,0]
	v_mov_b32_e32 v22, v21
	v_mov_b32_e32 v23, v17
	v_mov_b32_e32 v18, v20
	v_mov_b32_e32 v19, v16
	v_pk_mul_f32 v[22:23], v[22:23], v[22:23]
	s_nop 0
	v_pk_fma_f32 v[18:19], v[18:19], v[18:19], v[22:23]
	s_nop 0
	v_add_f32_e32 v18, v18, v19
	ds_bpermute_b32 v19, v10, v18
	s_waitcnt lgkmcnt(0)
	v_add_f32_e32 v18, v18, v19
	ds_bpermute_b32 v19, v11, v18
	s_waitcnt lgkmcnt(0)
	v_add_f32_e32 v18, v18, v19
	ds_bpermute_b32 v19, v12, v18
	s_waitcnt lgkmcnt(0)
	v_add_f32_e32 v18, v18, v19
	ds_bpermute_b32 v19, v13, v18
	s_waitcnt lgkmcnt(0)
	v_add_f32_e32 v18, v18, v19
	ds_bpermute_b32 v19, v149, v18
	s_waitcnt lgkmcnt(0)
	v_add_f32_e32 v18, v18, v19
	v_fmamk_f32 v18, v18, 0x3c000000, v15
	v_mul_f32_e32 v19, 0x4b800000, v18
	v_cmp_gt_f32_e32 vcc, s5, v18
	s_nop 1
	v_cndmask_b32_e32 v18, v18, v19, vcc
	v_rsq_f32_e32 v18, v18
	s_nop 0
	v_mul_f32_e32 v19, 0x45800000, v18
	v_cndmask_b32_e32 v18, v18, v19, vcc
	v_pk_mul_f32 v[20:21], v[20:21], v[18:19] op_sel_hi:[1,0]
	v_pk_mul_f32 v[16:17], v[16:17], v[18:19] op_sel_hi:[1,0]
	v_pk_mul_f32 v[18:19], v[8:9], v[20:21]
	v_pk_mul_f32 v[16:17], v[6:7], v[16:17]
	v_cvt_pk_bf16_f32 v18, v18, v19
	s_nop 0
	v_cvt_pk_bf16_f32 v19, v16, v17
	s_nop 1
	v_mov_b32_dpp v60, v18 quad_perm:[1,0,3,2] row_mask:0xf bank_mask:0xf
	v_mov_b32_dpp v61, v19 quad_perm:[1,0,3,2] row_mask:0xf bank_mask:0xf
	v_mov_b32_e32 v58, v18
	v_mov_b32_e32 v59, v19
	s_mov_b64 s[94:95], exec
	s_mov_b64 exec, s[92:93]
	global_store_dwordx4 v[2:3], v[58:61], off offset:-512 sc0 sc1
	s_mov_b64 exec, s[94:95]
	v_mov_b64_e32 v[16:17], v[32:33]
	v_mov_b64_e32 v[18:19], v[34:35]
	v_lshlrev_b32_e32 v20, 16, v16
	v_and_b32_e32 v21, 0xffff0000, v16
	v_lshlrev_b32_e32 v22, 16, v18
	v_and_b32_e32 v23, 0xffff0000, v18
	v_lshlrev_b32_e32 v16, 16, v17
	v_and_b32_e32 v17, 0xffff0000, v17
	v_lshlrev_b32_e32 v18, 16, v19
	v_and_b32_e32 v19, 0xffff0000, v19
	v_pk_fma_f32 v[20:21], v[4:5], v[22:23], v[20:21] neg_lo:[1,0,0] neg_hi:[1,0,0]
	v_pk_fma_f32 v[16:17], v[4:5], v[18:19], v[16:17] neg_lo:[1,0,0] neg_hi:[1,0,0]
	v_mov_b32_e32 v22, v21
	v_mov_b32_e32 v23, v17
	v_mov_b32_e32 v18, v20
	v_mov_b32_e32 v19, v16
	v_pk_mul_f32 v[22:23], v[22:23], v[22:23]
	s_nop 0
	v_pk_fma_f32 v[18:19], v[18:19], v[18:19], v[22:23]
	s_nop 0
	v_add_f32_e32 v18, v18, v19
	ds_bpermute_b32 v19, v10, v18
	s_waitcnt lgkmcnt(0)
	v_add_f32_e32 v18, v18, v19
	ds_bpermute_b32 v19, v11, v18
	s_waitcnt lgkmcnt(0)
	v_add_f32_e32 v18, v18, v19
	ds_bpermute_b32 v19, v12, v18
	s_waitcnt lgkmcnt(0)
	v_add_f32_e32 v18, v18, v19
	ds_bpermute_b32 v19, v13, v18
	s_waitcnt lgkmcnt(0)
	v_add_f32_e32 v18, v18, v19
	ds_bpermute_b32 v19, v149, v18
	s_waitcnt lgkmcnt(0)
	v_add_f32_e32 v18, v18, v19
	v_fmamk_f32 v18, v18, 0x3c000000, v15
	v_mul_f32_e32 v19, 0x4b800000, v18
	v_cmp_gt_f32_e32 vcc, s5, v18
	s_nop 1
	v_cndmask_b32_e32 v18, v18, v19, vcc
	v_rsq_f32_e32 v18, v18
	s_nop 0
	v_mul_f32_e32 v19, 0x45800000, v18
	v_cndmask_b32_e32 v18, v18, v19, vcc
	v_pk_mul_f32 v[20:21], v[20:21], v[18:19] op_sel_hi:[1,0]
	v_pk_mul_f32 v[16:17], v[16:17], v[18:19] op_sel_hi:[1,0]
	v_pk_mul_f32 v[18:19], v[8:9], v[20:21]
	v_pk_mul_f32 v[16:17], v[6:7], v[16:17]
	v_cvt_pk_bf16_f32 v18, v18, v19
	s_nop 0
	v_cvt_pk_bf16_f32 v19, v16, v17
	s_nop 1
	v_mov_b32_dpp v60, v18 quad_perm:[1,0,3,2] row_mask:0xf bank_mask:0xf
	v_mov_b32_dpp v61, v19 quad_perm:[1,0,3,2] row_mask:0xf bank_mask:0xf
	v_mov_b32_e32 v58, v18
	v_mov_b32_e32 v59, v19
	s_mov_b64 s[94:95], exec
	s_mov_b64 exec, s[92:93]
	global_store_dwordx4 v[2:3], v[58:61], off sc0 sc1
	s_mov_b64 exec, s[94:95]
	v_mov_b64_e32 v[16:17], v[36:37]
	v_mov_b64_e32 v[18:19], v[38:39]
	v_lshlrev_b32_e32 v20, 16, v16
	v_and_b32_e32 v21, 0xffff0000, v16
	v_lshlrev_b32_e32 v22, 16, v18
	v_and_b32_e32 v23, 0xffff0000, v18
	v_lshlrev_b32_e32 v16, 16, v17
	v_and_b32_e32 v17, 0xffff0000, v17
	v_lshlrev_b32_e32 v18, 16, v19
	v_and_b32_e32 v19, 0xffff0000, v19
	v_pk_fma_f32 v[20:21], v[4:5], v[22:23], v[20:21] neg_lo:[1,0,0] neg_hi:[1,0,0]
	v_pk_fma_f32 v[16:17], v[4:5], v[18:19], v[16:17] neg_lo:[1,0,0] neg_hi:[1,0,0]
	v_mov_b32_e32 v22, v21
	v_mov_b32_e32 v23, v17
	v_mov_b32_e32 v18, v20
	v_mov_b32_e32 v19, v16
	v_pk_mul_f32 v[22:23], v[22:23], v[22:23]
	s_nop 0
	v_pk_fma_f32 v[18:19], v[18:19], v[18:19], v[22:23]
	s_nop 0
	v_add_f32_e32 v18, v18, v19
	ds_bpermute_b32 v19, v10, v18
	s_waitcnt lgkmcnt(0)
	v_add_f32_e32 v18, v18, v19
	ds_bpermute_b32 v19, v11, v18
	s_waitcnt lgkmcnt(0)
	v_add_f32_e32 v18, v18, v19
	ds_bpermute_b32 v19, v12, v18
	s_waitcnt lgkmcnt(0)
	v_add_f32_e32 v18, v18, v19
	ds_bpermute_b32 v19, v13, v18
	s_waitcnt lgkmcnt(0)
	v_add_f32_e32 v18, v18, v19
	ds_bpermute_b32 v19, v149, v18
	s_waitcnt lgkmcnt(0)
	v_add_f32_e32 v18, v18, v19
	v_fmamk_f32 v18, v18, 0x3c000000, v15
	v_mul_f32_e32 v19, 0x4b800000, v18
	v_cmp_gt_f32_e32 vcc, s5, v18
	s_nop 1
	v_cndmask_b32_e32 v18, v18, v19, vcc
	v_rsq_f32_e32 v18, v18
	s_nop 0
	v_mul_f32_e32 v19, 0x45800000, v18
	v_cndmask_b32_e32 v18, v18, v19, vcc
	v_pk_mul_f32 v[20:21], v[20:21], v[18:19] op_sel_hi:[1,0]
	v_pk_mul_f32 v[16:17], v[16:17], v[18:19] op_sel_hi:[1,0]
	v_pk_mul_f32 v[18:19], v[8:9], v[20:21]
	v_pk_mul_f32 v[16:17], v[6:7], v[16:17]
	v_cvt_pk_bf16_f32 v18, v18, v19
	s_nop 0
	v_cvt_pk_bf16_f32 v19, v16, v17
	s_nop 1
	v_mov_b32_dpp v60, v18 quad_perm:[1,0,3,2] row_mask:0xf bank_mask:0xf
	v_mov_b32_dpp v61, v19 quad_perm:[1,0,3,2] row_mask:0xf bank_mask:0xf
	v_mov_b32_e32 v58, v18
	v_mov_b32_e32 v59, v19
	s_mov_b64 s[94:95], exec
	s_mov_b64 exec, s[92:93]
	global_store_dwordx4 v[2:3], v[58:61], off offset:512 sc0 sc1
	s_mov_b64 exec, s[94:95]
	v_lshl_add_u64 v[2:3], v[2:3], 0, s[8:9]
	s_cbranch_scc0 .Lcb_done
	s_waitcnt vmcnt(4)
	v_mov_b64_e32 v[24:25], v[40:41]
	v_mov_b64_e32 v[26:27], v[42:43]
	v_mov_b64_e32 v[28:29], v[44:45]
	v_mov_b64_e32 v[30:31], v[46:47]
	v_mov_b64_e32 v[32:33], v[48:49]
	v_mov_b64_e32 v[34:35], v[50:51]
	v_mov_b64_e32 v[36:37], v[52:53]
	v_mov_b64_e32 v[38:39], v[54:55]
	s_branch .LBB0_1531
